# v47 + SGU transposed LN tile XOR-swizzled in LDS (16-way -> 2-way bank conflicts on the 2-byte transposing stores)
# speedup vs baseline: 1.0253x; 1.0077x over previous
.LBB0_249:
	s_or_b64 exec, exec, s[8:9]
	v_lshl_add_u32 v50, v73, 1, 0
	s_movk_i32 s14, 0x110
	v_cvt_pk_bf16_f32 v22, v22, v23
	v_cvt_pk_bf16_f32 v23, v24, v25
	v_cvt_pk_bf16_f32 v24, v18, v19
	s_waitcnt lgkmcnt(1)
	v_mad_u64_u32 v[18:19], s[8:9], v74, s14, v[50:51]
	v_cvt_pk_bf16_f32 v25, v20, v21
	ds_write_b128 v18, v[22:25]
	v_mad_u64_u32 v[22:23], s[8:9], v71, s14, v[50:51]
	v_cvt_pk_bf16_f32 v18, v30, v31
	v_cvt_pk_bf16_f32 v19, v32, v33
	v_cvt_pk_bf16_f32 v20, v26, v27
	v_cvt_pk_bf16_f32 v21, v28, v29
	ds_write_b128 v22, v[18:21]
	v_mad_u64_u32 v[22:23], s[8:9], v70, s14, v[50:51]
	v_cvt_pk_bf16_f32 v18, v38, v39
	v_cvt_pk_bf16_f32 v19, v40, v41
	v_cvt_pk_bf16_f32 v20, v34, v35
	v_cvt_pk_bf16_f32 v21, v36, v37
	ds_write_b128 v22, v[18:21]
	v_mad_u64_u32 v[22:23], s[8:9], v69, s14, v[50:51]
	v_cvt_pk_bf16_f32 v18, v46, v47
	v_cvt_pk_bf16_f32 v19, v48, v49
	v_cvt_pk_bf16_f32 v20, v42, v43
	v_cvt_pk_bf16_f32 v21, v44, v45
	ds_write_b128 v22, v[18:21]
	s_waitcnt lgkmcnt(0)
	s_barrier
	s_load_dwordx2 s[8:9], s[0:1], 0xa0
	v_readlane_b32 s16, v255, 38
	v_readlane_b32 s17, v255, 39
	s_lshl_b64 s[12:13], s[16:17], 2
	v_and_b32_e32 v26, 0xffff0000, v14
	s_waitcnt lgkmcnt(0)
	s_add_u32 s8, s8, s12
	s_addc_u32 s9, s9, s13
	s_lshl_b32 s12, s7, 2
	s_add_u32 s8, s8, s12
	s_addc_u32 s9, s9, 0
	global_load_dwordx4 v[22:25], v0, s[8:9]
	global_load_dwordx4 v[18:21], v0, s[8:9] offset:16
	s_add_i32 s12, 0, 0x20000
	v_lshlrev_b32_e32 v0, 16, v14
	v_lshl_add_u32 v14, v74, 2, s12
	v_lshlrev_b32_e32 v27, 16, v15
	v_and_b32_e32 v28, 0xffff0000, v15
	ds_read2st64_b32 v[14:15], v14 offset1:2
	v_lshlrev_b32_e32 v29, 16, v16
	v_and_b32_e32 v16, 0xffff0000, v16
	v_lshlrev_b32_e32 v30, 16, v17
	v_and_b32_e32 v17, 0xffff0000, v17
	s_waitcnt lgkmcnt(0)
	v_sub_f32_e32 v0, v0, v14
	v_sub_f32_e32 v26, v26, v14
	v_sub_f32_e32 v27, v27, v14
	v_sub_f32_e32 v28, v28, v14
	v_sub_f32_e32 v29, v29, v14
	v_sub_f32_e32 v16, v16, v14
	v_sub_f32_e32 v30, v30, v14
	v_sub_f32_e32 v14, v17, v14
	v_mul_f32_e32 v0, v15, v0
	v_mul_f32_e32 v17, v15, v26
	v_mul_f32_e32 v26, v15, v27
	v_mul_f32_e32 v27, v15, v28
	v_mul_f32_e32 v28, v15, v29
	v_mul_f32_e32 v16, v15, v16
	v_mul_f32_e32 v29, v15, v30
	v_mul_f32_e32 v14, v15, v14
	v_xor_b32_e32 v31, v74, v73
	v_lshlrev_b32_e32 v31, 1, v31
	v_mul_u32_u24_e32 v32, 0x110, v73
	v_add3_u32 v31, 0, v31, v32
	s_load_dwordx2 s[8:9], s[0:1], 0xb0
	s_add_i32 s11, s11, 16
	s_lshl_b32 s6, s6, 7
	s_waitcnt vmcnt(1)
	v_mul_f32_e32 v0, v22, v0
	v_mul_f32_e32 v15, v23, v17
	v_mul_f32_e32 v17, v24, v26
	v_mul_f32_e32 v26, v25, v27
	s_waitcnt vmcnt(0)
	v_mul_f32_e32 v27, v18, v28
	v_mul_f32_e32 v16, v19, v16
	v_mul_f32_e32 v28, v20, v29
	v_mul_f32_e32 v29, v21, v14
	v_bfe_u32 v14, v0, 16, 1
	v_bfe_u32 v30, v15, 16, 1
	v_bfe_u32 v33, v17, 16, 1
	v_bfe_u32 v34, v26, 16, 1
	v_bfe_u32 v35, v27, 16, 1
	v_bfe_u32 v36, v16, 16, 1
	v_add3_u32 v0, v0, v14, s90
	v_add3_u32 v14, v15, v30, s90
	v_add3_u32 v15, v17, v33, s90
	v_add3_u32 v17, v26, v34, s90
	v_add3_u32 v26, v27, v35, s90
	v_add3_u32 v16, v16, v36, s90
	ds_write_b16_d16_hi v31, v0 offset:34816
	ds_write_b16_d16_hi v31, v14 offset:35088
	ds_write_b16_d16_hi v31, v15 offset:35360
	ds_write_b16_d16_hi v31, v17 offset:35632
	ds_write_b16_d16_hi v31, v26 offset:35904
	ds_write_b16_d16_hi v31, v16 offset:36176
	v_bfe_u32 v0, v28, 16, 1
	v_add3_u32 v0, v28, v0, s90
	ds_write_b16_d16_hi v31, v0 offset:36448
	v_lshl_add_u32 v0, v71, 2, s12
	ds_read2st64_b32 v[14:15], v0 offset1:2
	v_bfe_u32 v0, v29, 16, 1
	v_add3_u32 v0, v29, v0, s90
	ds_write_b16_d16_hi v31, v0 offset:36720
	v_lshlrev_b32_e32 v0, 16, v10
	s_waitcnt lgkmcnt(0)
	v_sub_f32_e32 v0, v0, v14
	v_mul_f32_e32 v0, v15, v0
	v_and_b32_e32 v10, 0xffff0000, v10
	v_lshlrev_b32_e32 v16, 16, v11
	v_and_b32_e32 v11, 0xffff0000, v11
	v_lshlrev_b32_e32 v17, 16, v12
	v_and_b32_e32 v12, 0xffff0000, v12
	v_lshlrev_b32_e32 v26, 16, v13
	v_and_b32_e32 v13, 0xffff0000, v13
	v_mul_f32_e32 v0, v22, v0
	v_sub_f32_e32 v10, v10, v14
	v_sub_f32_e32 v16, v16, v14
	v_sub_f32_e32 v11, v11, v14
	v_sub_f32_e32 v17, v17, v14
	v_sub_f32_e32 v12, v12, v14
	v_sub_f32_e32 v26, v26, v14
	v_sub_f32_e32 v13, v13, v14
	v_mul_f32_e32 v10, v15, v10
	v_mul_f32_e32 v16, v15, v16
	v_mul_f32_e32 v11, v15, v11
	v_mul_f32_e32 v17, v15, v17
	v_mul_f32_e32 v12, v15, v12
	v_mul_f32_e32 v26, v15, v26
	v_mul_f32_e32 v13, v15, v13
	v_xor_b32_e32 v14, v71, v73
	v_lshlrev_b32_e32 v14, 1, v14
	v_bfe_u32 v15, v0, 16, 1
	v_mul_f32_e32 v10, v23, v10
	v_add3_u32 v0, v0, v15, s90
	v_add3_u32 v14, 0, v14, v32
	ds_write_b16_d16_hi v14, v0 offset:34816
	v_bfe_u32 v0, v10, 16, 1
	v_mul_f32_e32 v16, v24, v16
	v_add3_u32 v0, v10, v0, s90
	ds_write_b16_d16_hi v14, v0 offset:35088
	v_bfe_u32 v0, v16, 16, 1
	v_mul_f32_e32 v11, v25, v11
	v_add3_u32 v0, v16, v0, s90
	ds_write_b16_d16_hi v14, v0 offset:35360
	v_bfe_u32 v0, v11, 16, 1
	v_mul_f32_e32 v17, v18, v17
	v_add3_u32 v0, v11, v0, s90
	ds_write_b16_d16_hi v14, v0 offset:35632
	v_bfe_u32 v0, v17, 16, 1
	v_mul_f32_e32 v12, v19, v12
	v_add3_u32 v0, v17, v0, s90
	ds_write_b16_d16_hi v14, v0 offset:35904
	v_bfe_u32 v0, v12, 16, 1
	v_mul_f32_e32 v26, v20, v26
	v_add3_u32 v0, v12, v0, s90
	ds_write_b16_d16_hi v14, v0 offset:36176
	v_bfe_u32 v0, v26, 16, 1
	v_add3_u32 v0, v26, v0, s90
	ds_write_b16_d16_hi v14, v0 offset:36448
	v_lshl_add_u32 v0, v70, 2, s12
	ds_read2st64_b32 v[10:11], v0 offset1:2
	v_mul_f32_e32 v13, v21, v13
	v_bfe_u32 v0, v13, 16, 1
	v_add3_u32 v0, v13, v0, s90
	ds_write_b16_d16_hi v14, v0 offset:36720
	v_lshlrev_b32_e32 v0, 16, v6
	s_waitcnt lgkmcnt(1)
	v_sub_f32_e32 v0, v0, v10
	v_mul_f32_e32 v0, v11, v0
	v_and_b32_e32 v6, 0xffff0000, v6
	v_lshlrev_b32_e32 v12, 16, v7
	v_and_b32_e32 v7, 0xffff0000, v7
	v_lshlrev_b32_e32 v13, 16, v8
	v_and_b32_e32 v8, 0xffff0000, v8
	v_lshlrev_b32_e32 v14, 16, v9
	v_and_b32_e32 v9, 0xffff0000, v9
	v_mul_f32_e32 v0, v22, v0
	v_sub_f32_e32 v6, v6, v10
	v_sub_f32_e32 v12, v12, v10
	v_sub_f32_e32 v7, v7, v10
	v_sub_f32_e32 v13, v13, v10
	v_sub_f32_e32 v8, v8, v10
	v_sub_f32_e32 v14, v14, v10
	v_sub_f32_e32 v9, v9, v10
	v_mul_f32_e32 v6, v11, v6
	v_mul_f32_e32 v12, v11, v12
	v_mul_f32_e32 v7, v11, v7
	v_mul_f32_e32 v13, v11, v13
	v_mul_f32_e32 v8, v11, v8
	v_mul_f32_e32 v14, v11, v14
	v_mul_f32_e32 v9, v11, v9
	v_xor_b32_e32 v10, v70, v73
	v_lshlrev_b32_e32 v10, 1, v10
	v_bfe_u32 v11, v0, 16, 1
	v_mul_f32_e32 v6, v23, v6
	v_add3_u32 v0, v0, v11, s90
	v_add3_u32 v10, 0, v10, v32
	ds_write_b16_d16_hi v10, v0 offset:34816
	v_bfe_u32 v0, v6, 16, 1
	v_mul_f32_e32 v12, v24, v12
	v_add3_u32 v0, v6, v0, s90
	ds_write_b16_d16_hi v10, v0 offset:35088
	v_bfe_u32 v0, v12, 16, 1
	v_mul_f32_e32 v7, v25, v7
	v_add3_u32 v0, v12, v0, s90
	ds_write_b16_d16_hi v10, v0 offset:35360
	v_bfe_u32 v0, v7, 16, 1
	v_mul_f32_e32 v13, v18, v13
	v_add3_u32 v0, v7, v0, s90
	ds_write_b16_d16_hi v10, v0 offset:35632
	v_bfe_u32 v0, v13, 16, 1
	v_mul_f32_e32 v8, v19, v8
	v_add3_u32 v0, v13, v0, s90
	ds_write_b16_d16_hi v10, v0 offset:35904
	v_bfe_u32 v0, v8, 16, 1
	v_mul_f32_e32 v14, v20, v14
	v_add3_u32 v0, v8, v0, s90
	ds_write_b16_d16_hi v10, v0 offset:36176
	v_bfe_u32 v0, v14, 16, 1
	v_add3_u32 v0, v14, v0, s90
	ds_write_b16_d16_hi v10, v0 offset:36448
	v_lshl_add_u32 v0, v69, 2, s12
	ds_read2st64_b32 v[6:7], v0 offset1:2
	v_mul_f32_e32 v9, v21, v9
	v_bfe_u32 v0, v9, 16, 1
	v_add3_u32 v0, v9, v0, s90
	ds_write_b16_d16_hi v10, v0 offset:36720
	v_lshlrev_b32_e32 v0, 16, v2
	s_waitcnt lgkmcnt(1)
	v_sub_f32_e32 v0, v0, v6
	v_mul_f32_e32 v0, v7, v0
	v_and_b32_e32 v2, 0xffff0000, v2
	v_lshlrev_b32_e32 v8, 16, v3
	v_and_b32_e32 v3, 0xffff0000, v3
	v_lshlrev_b32_e32 v9, 16, v4
	v_and_b32_e32 v4, 0xffff0000, v4
	v_lshlrev_b32_e32 v10, 16, v5
	v_and_b32_e32 v5, 0xffff0000, v5
	v_mul_f32_e32 v0, v22, v0
	v_sub_f32_e32 v2, v2, v6
	v_sub_f32_e32 v8, v8, v6
	v_sub_f32_e32 v3, v3, v6
	v_sub_f32_e32 v9, v9, v6
	v_sub_f32_e32 v4, v4, v6
	v_sub_f32_e32 v10, v10, v6
	v_sub_f32_e32 v5, v5, v6
	v_mul_f32_e32 v2, v7, v2
	v_mul_f32_e32 v8, v7, v8
	v_mul_f32_e32 v3, v7, v3
	v_mul_f32_e32 v9, v7, v9
	v_mul_f32_e32 v4, v7, v4
	v_mul_f32_e32 v10, v7, v10
	v_mul_f32_e32 v5, v7, v5
	v_xor_b32_e32 v6, v69, v73
	v_lshlrev_b32_e32 v6, 1, v6
	v_bfe_u32 v7, v0, 16, 1
	v_mul_f32_e32 v2, v23, v2
	v_add3_u32 v0, v0, v7, s90
	v_add3_u32 v6, 0, v6, v32
	ds_write_b16_d16_hi v6, v0 offset:34816
	v_bfe_u32 v0, v2, 16, 1
	v_mul_f32_e32 v8, v24, v8
	v_add3_u32 v0, v2, v0, s90
	ds_write_b16_d16_hi v6, v0 offset:35088
	v_bfe_u32 v0, v8, 16, 1
	v_mul_f32_e32 v3, v25, v3
	v_add3_u32 v0, v8, v0, s90
	ds_write_b16_d16_hi v6, v0 offset:35360
	v_bfe_u32 v0, v3, 16, 1
	v_mul_f32_e32 v9, v18, v9
	v_add3_u32 v0, v3, v0, s90
	ds_write_b16_d16_hi v6, v0 offset:35632
	v_bfe_u32 v0, v9, 16, 1
	v_mul_f32_e32 v4, v19, v4
	v_add3_u32 v0, v9, v0, s90
	ds_write_b16_d16_hi v6, v0 offset:35904
	v_bfe_u32 v0, v4, 16, 1
	v_mul_f32_e32 v10, v20, v10
	v_add3_u32 v0, v4, v0, s90
	ds_write_b16_d16_hi v6, v0 offset:36176
	v_bfe_u32 v0, v10, 16, 1
	v_mul_f32_e32 v5, v21, v5
	v_add3_u32 v0, v10, v0, s90
	ds_write_b16_d16_hi v6, v0 offset:36448
	v_bfe_u32 v0, v5, 16, 1
	v_add3_u32 v0, v5, v0, s90
	ds_write_b16_d16_hi v6, v0 offset:36720
	v_bfe_u32 v18, v68, 4, 2
	v_bfi_b32 v0, -16, v72, v68
	v_and_b32_e32 v200, 0x18, v0
	v_lshrrev_b32_e32 v201, 5, v0
	v_lshlrev_b32_e32 v200, 1, v200
	v_and_b32_e32 v201, 3, v201
	v_and_b32_e32 v19, -16, v72
	v_mul_lo_u32 v0, v0, s14
	v_lshlrev_b32_e32 v22, 4, v18
	v_lshlrev_b32_e32 v201, 6, v201
	v_xor_b32_e32 v200, v22, v200
	v_add3_u32 v0, 0, v0, v200
	v_xor_b32_e32 v203, 64, v201
	v_xor_b32_e32 v204, 0x80, v201
	v_xor_b32_e32 v205, 0xc0, v201
	v_add_u32_e32 v202, v0, v201
	v_add_u32_e32 v203, v0, v203
	v_add_u32_e32 v204, v0, v204
	v_add_u32_e32 v205, v0, v205
	v_lshl_or_b32 v18, v18, 2, v19
	s_waitcnt lgkmcnt(0)
	s_barrier
	v_and_b32_e32 v23, 15, v68
	ds_read_b128 v[2:5], v202 offset:34816
	ds_read_b128 v[6:9], v203 offset:34816
	ds_read_b128 v[10:13], v204 offset:34816
	ds_read_b128 v[14:17], v205 offset:34816
	v_mov_b32_e32 v0, s20
	v_ashrrev_i32_e32 v19, 31, v18
	v_lshl_add_u64 v[24:25], v[18:19], 1, v[0:1]
	v_add_lshl_u32 v0, s11, v23, 11
	s_ashr_i32 s12, s6, 31
	v_or_b32_e32 v20, s6, v23
	v_lshl_add_u64 v[18:19], v[24:25], 0, v[0:1]
	v_mul_u32_u24_e32 v0, 0x110, v23
	s_add_i32 s6, s16, s7
	v_add3_u32 v26, v0, v22, 0
	v_add_u32_e32 v22, s6, v23
	s_lshl_b32 s6, s10, 16
	s_and_b32 s6, s6, 0x3fc0000
	v_mov_b32_e32 v21, s12
	v_lshl_or_b32 v0, v23, 11, s6
	v_lshl_add_u64 v[20:21], v[20:21], 2, s[8:9]
	v_lshl_add_u64 v[24:25], v[24:25], 0, v[0:1]
	v_lshl_add_u64 v[18:19], s[64:65], 0, v[18:19]
	v_lshl_add_u64 v[20:21], v[20:21], 0, 64
	v_lshl_add_u64 v[24:25], s[64:65], 0, v[24:25]
	s_mov_b64 s[6:7], 0
